# unified group sub-counters: one arrival per sync; waits after GLU/out-proj/gate-up/down (except last layer) poll only the own group's word, the others all eight
# speedup vs baseline: 1.0232x; 1.0043x over previous
; __device__ __forceinline__ CArgs* get_args() { CArgs* p = (CArgs*)__builtin_amdgcn_kernarg_segment_ptr(); asm volatile("" : "+s"(p)); return p; }
; __global__ void __launch_bounds__(512, 2) hymba_fwd(Args A_unused) {
;     ...
;     const int wave0 = __builtin_amdgcn_readfirstlane(threadIdx.x >> 6);
;     ...
;     unsigned nsync = 0;
;     ...
;     { PHASE_IDS(); if (blk == 0 && tid == 0) __hip_atomic_store((unsigned*)(get_args()->ws + WS_CTL), 0u, __ATOMIC_RELAXED, __HIP_MEMORY_SCOPE_AGENT);
_Z9hymba_fwd4Args:
	s_load_dword s67, s[0:1], 0xe0
	s_mov_b64 s[68:69], s[0:1]
	v_and_b32_e32 v1, 0x3ff, v0
	s_add_u32 s6, s68, 0xe0
	v_readfirstlane_b32 s24, v1
	s_addc_u32 s7, s69, 0
	s_lshr_b32 s77, s24, 6
	s_mov_b32 s76, s2
	s_mov_b32 s0, s77
	v_mbcnt_lo_u32_b32 v2, -1, 0
	v_mbcnt_hi_u32_b32 v2, -1, v2
	s_waitcnt lgkmcnt(0)
	s_mov_b32 s2, s67
	v_lshl_add_u32 v3, s0, 6, v2
	s_mov_b32 s4, s76
	s_nop 0
	v_or_b32_e32 v2, s4, v3
	v_readfirstlane_b32 s3, v3
	v_cmp_eq_u32_e32 vcc, 0, v2
	s_and_saveexec_b64 s[0:1], vcc
	s_cbranch_execz .LBB0_2
	s_mov_b64 s[8:9], s[68:69]
	s_load_dwordx2 s[8:9], s[8:9], 0xd8
	v_mov_b32_e32 v2, 0
	s_waitcnt lgkmcnt(0)
	global_store_dword v2, v2, s[8:9] sc1
	global_store_dword v2, v2, s[8:9] offset:1024 sc1
	global_store_dword v2, v2, s[8:9] offset:1088 sc1
	global_store_dword v2, v2, s[8:9] offset:1152 sc1
	global_store_dword v2, v2, s[8:9] offset:1216 sc1
	global_store_dword v2, v2, s[8:9] offset:1280 sc1
	global_store_dword v2, v2, s[8:9] offset:1344 sc1
	global_store_dword v2, v2, s[8:9] offset:1408 sc1
	global_store_dword v2, v2, s[8:9] offset:1472 sc1

.LBB0_1325:
	s_or_b64 exec, exec, s[6:7]
	v_readlane_b32 s4, v254, 1
	s_add_i32 s6, s4, 4
	s_lshl_b32 s6, s6, 5
	s_and_b32 s4, s76, 7
	s_lshl_b32 s4, s4, 6
	s_add_i32 s4, s4, 0x400
	s_add_u32 s2, s2, s4
	s_addc_u32 s3, s3, 0
	s_mov_b32 s7, 0x400000
	s_branch .LBB0_1327

.LBB0_1381:
	s_or_b64 exec, exec, s[6:7]
	v_readlane_b32 s4, v254, 1
	s_add_i32 s6, s4, 5
	s_lshl_b32 s6, s6, 5
	s_and_b32 s4, s76, 7
	s_lshl_b32 s4, s4, 6
	s_add_i32 s4, s4, 0x400
	s_add_u32 s2, s2, s4
	s_addc_u32 s3, s3, 0
	s_mov_b32 s7, 0x400000
	s_branch .LBB0_1383

.LBB0_1453:
	s_or_b64 exec, exec, s[6:7]
	v_readlane_b32 s4, v254, 1
	s_add_i32 s6, s4, 6
	s_lshl_b32 s6, s6, 5
	s_and_b32 s4, s76, 7
	s_lshl_b32 s4, s4, 6
	s_add_i32 s4, s4, 0x400
	s_add_u32 s2, s2, s4
	s_addc_u32 s3, s3, 0
	s_mov_b32 s7, 0x400000
	s_branch .LBB0_1455

; __device__ __forceinline__ CArgs* get_args() { CArgs* p = (CArgs*)__builtin_amdgcn_kernarg_segment_ptr(); asm volatile("" : "+s"(p)); return p; }
; __global__ void __launch_bounds__(512, 2) hymba_fwd(Args A_unused) {
;     ...
;         PHASE_IDS(); CArgs* Ap = get_args();
;         const float* fr = (const float*)(Ap->ws + WS_RSQ) + (size_t)(2 * DEPTH) * RSQ_BUF; const float* gn = Ap->in[4]; float* out = Ap->out;
;         for (int m = gw; m < MTOK; m += NGW) {
;             const float sq = wave_sum(lane < 32 ? fr[(size_t)lane * MTOK + m] : 0.f);
.LBB0_1513:
	s_or_b64 exec, exec, s[6:7]
	v_readlane_b32 s4, v254, 1
	s_lshl_b32 s6, s4, 5
	s_mov_b32 s7, 0x80000
	s_cmp_eq_u32 s4, 28
	s_cbranch_scc1 .Ls7_glob
	s_and_b32 s5, s76, 7
	s_lshl_b32 s5, s5, 6
	s_add_i32 s5, s5, 0x400
	s_add_u32 s2, s2, s5
	s_addc_u32 s3, s3, 0
.Ls7_loc:
	global_load_dword v0, v145, s[2:3] sc1
	s_waitcnt vmcnt(0)
	v_cmp_le_u32_e32 vcc, s6, v0
	s_cbranch_vccnz .Lsyncinv_6
	s_sleep 2
	s_add_i32 s7, s7, -1
	s_cmp_lg_u32 s7, 0
	s_cbranch_scc1 .Ls7_loc
	s_branch .Lsyncinv_6
.Ls7_glob:
	global_load_dword v0, v145, s[2:3] offset:1024 sc1
	global_load_dword v1, v145, s[2:3] offset:1088 sc1
	global_load_dword v2, v145, s[2:3] offset:1152 sc1
	global_load_dword v3, v145, s[2:3] offset:1216 sc1
	global_load_dword v4, v145, s[2:3] offset:1280 sc1
	global_load_dword v5, v145, s[2:3] offset:1344 sc1
	global_load_dword v6, v145, s[2:3] offset:1408 sc1
	global_load_dword v7, v145, s[2:3] offset:1472 sc1
	s_waitcnt vmcnt(0)
	v_min3_u32 v0, v0, v1, v2
	v_min3_u32 v3, v3, v4, v5
	v_min3_u32 v0, v0, v6, v7
	v_min_u32_e32 v0, v0, v3
	v_cmp_le_u32_e32 vcc, s6, v0
	s_cbranch_vccnz .Lsyncinv_6
	s_sleep 2
	s_add_i32 s7, s7, -1
	s_cmp_lg_u32 s7, 0
	s_cbranch_scc1 .Ls7_glob
	s_branch .Lsyncinv_6
